# gate_up tile decode: runtime division by group size (always 8) replaced by shift/mask
# speedup vs baseline: 1.0186x; 1.0055x over previous
.LBB0_251:
	s_add_i32 s61, s62, 1
	s_mul_i32 s2, s61, s56
	s_mul_hi_u32 s3, s61, s57
	s_add_i32 s3, s3, s2
	s_mul_i32 s2, s61, s57
	s_add_u32 s22, s2, s96
	s_addc_u32 s23, s3, s35
	v_cmp_gt_i64_e32 vcc, s[22:23], v[152:153]
	v_cmp_lt_i64_e64 s[2:3], s[22:23], v[150:151]
	s_cbranch_vccnz .LBB0_253
	s_ashr_i32 s12, s22, 31
	s_lshr_b32 s12, s12, 29
	s_add_i32 s12, s22, s12
	s_ashr_i32 s13, s12, 3
	s_and_b32 s12, s12, -8
	s_sub_i32 s12, s22, s12
	s_cmp_lt_i32 s12, 0
	s_movk_i32 s20, 0x2c1
	s_cselect_b32 s20, s20, 0x2c0
	s_mul_i32 s12, s12, s20
	s_add_i32 s12, s12, s13
	s_mul_hi_i32 s13, s12, 0x2e8ba2e9
	s_lshr_b32 s20, s13, 31
	s_ashr_i32 s13, s13, 5
	s_add_i32 s13, s13, s20
	s_lshl_b32 s20, s13, 3
	s_mulk_i32 s13, 0xb0
	s_sub_i32 s13, s12, s13
	s_ashr_i32 s12, s13, 3
	s_and_b32 s13, s13, 7
	s_add_i32 s20, s20, s13

.LBB0_1066:
	s_add_i32 s53, s56, 1
	s_mul_i32 s2, s53, s43
	s_mul_hi_u32 s3, s53, s46
	s_add_i32 s3, s3, s2
	s_mul_i32 s2, s53, s46
	s_add_u32 s18, s2, s96
	s_addc_u32 s19, s3, s34
	v_cmp_gt_i64_e32 vcc, s[18:19], v[150:151]
	v_cmp_lt_i64_e64 s[2:3], s[18:19], v[148:149]
	s_cbranch_vccnz .LBB0_1068
	s_ashr_i32 s14, s18, 31
	s_lshr_b32 s14, s14, 29
	s_add_i32 s14, s18, s14
	s_ashr_i32 s15, s14, 3
	s_and_b32 s14, s14, -8
	s_sub_i32 s14, s18, s14
	s_cmp_lt_i32 s14, 0
	s_cselect_b32 s16, s47, 0x2c0
	s_mul_i32 s14, s14, s16
	s_add_i32 s14, s14, s15
	s_mul_hi_i32 s15, s14, 0x2e8ba2e9
	s_lshr_b32 s16, s15, 31
	s_ashr_i32 s15, s15, 5
	s_add_i32 s15, s15, s16
	s_lshl_b32 s16, s15, 3
	s_mulk_i32 s15, 0xb0
	s_sub_i32 s15, s14, s15
	s_ashr_i32 s14, s15, 3
	s_and_b32 s15, s15, 7
	s_add_i32 s16, s16, s15

.LBB0_1358:
	s_add_i32 s55, s56, 1
	s_mul_i32 s2, s55, s47
	s_mul_hi_u32 s3, s55, s48
	s_add_i32 s3, s3, s2
	s_mul_i32 s2, s55, s48
	s_add_u32 s18, s2, s96
	s_addc_u32 s19, s3, s34
	v_cmp_gt_i64_e32 vcc, s[18:19], v[142:143]
	v_cmp_lt_i64_e64 s[2:3], s[18:19], v[140:141]
	s_cbranch_vccnz .LBB0_1360
	s_ashr_i32 s6, s18, 31
	s_lshr_b32 s6, s6, 29
	s_add_i32 s6, s18, s6
	s_ashr_i32 s7, s6, 3
	s_and_b32 s6, s6, -8
	s_sub_i32 s6, s18, s6
	s_cmp_lt_i32 s6, 0
	s_cselect_b32 s16, s49, 0x2c0
	s_mul_i32 s6, s6, s16
	s_add_i32 s6, s6, s7
	s_mul_hi_i32 s7, s6, 0x2e8ba2e9
	s_lshr_b32 s16, s7, 31
	s_ashr_i32 s7, s7, 5
	s_add_i32 s7, s7, s16
	s_lshl_b32 s16, s7, 3
	s_mulk_i32 s7, 0xb0
	s_sub_i32 s7, s6, s7
	s_ashr_i32 s6, s7, 3
	s_and_b32 s7, s7, 7
	s_add_i32 s16, s16, s7

.LBB0_1934:
	s_add_i32 s49, s52, 1
	s_mul_i32 s2, s49, s41
	s_mul_hi_u32 s3, s49, s42
	s_add_i32 s3, s3, s2
	s_mul_i32 s2, s49, s42
	s_add_u32 s14, s2, s96
	s_addc_u32 s15, s3, s28
	v_cmp_gt_i64_e32 vcc, s[14:15], v[150:151]
	v_cmp_lt_i64_e64 s[2:3], s[14:15], v[148:149]
	s_cbranch_vccnz .LBB0_1936
	s_ashr_i32 s10, s14, 31
	s_lshr_b32 s10, s10, 29
	s_add_i32 s10, s14, s10
	s_ashr_i32 s11, s10, 3
	s_and_b32 s10, s10, -8
	s_sub_i32 s10, s14, s10
	s_cmp_lt_i32 s10, 0
	s_cselect_b32 s12, s43, 0x2c0
	s_mul_i32 s10, s10, s12
	s_add_i32 s10, s10, s11
	s_mul_hi_i32 s11, s10, 0x2e8ba2e9
	s_lshr_b32 s12, s11, 31
	s_ashr_i32 s11, s11, 5
	s_add_i32 s11, s11, s12
	s_lshl_b32 s12, s11, 3
	s_mulk_i32 s11, 0xb0
	s_sub_i32 s11, s10, s11
	s_ashr_i32 s10, s11, 3
	s_and_b32 s11, s11, 7
	s_add_i32 s12, s12, s11
